# hand-written chunk-state scan (LDS-transposed decay block, loads two half-rounds ahead) plus pipelined sample up-projection in P3
# baseline (speedup 1.0000x reference)
; DI float bf2f(bf16_t v) { return __uint_as_float(((unsigned)v) << 16); }
; DI void p3_scan(const Params& p) {
;     ...
;     const float* dec = (const float*)(p.ws + OFF_DEC);
;     for (int w = gw; w < 1024; w += NGW) {
;         const int bh = w & 7, idx = (w >> 3) * 64 + lane, dk = idx & 63, dv = idx >> 6;
;         const bf16_t* sl = (const bf16_t*)(p.out + O_Y) + (size_t)bh * 128 * 8192 + idx;
;         bf16_t* sp = (bf16_t*)(p.out + O_SPB) + (size_t)bh * 128 * 8192 + (size_t)((((dv >> 5) * 4 + (dk >> 4)) * 2 + ((dk >> 3) & 1)) * 32 + (dv & 31)) * 8 + (dk & 7);
;         const float* dc = dec + (size_t)bh * 128 * 64 + dk;
;         float S = 0.f;
;         for (int c0 = 0; c0 < 128; c0 += 32) {
;             float v[32], d[32];
; #pragma unroll
;             for (int j = 0; j < 32; ++j) { v[j] = bf2f(sl[(size_t)(c0 + j) * 8192]); d[j] = dc[(c0 + j) * 64]; }
.LBB0_1064:
	s_or_b64 exec, exec, s[4:5]
	v_mov_b32_e32 v14, v203
	s_waitcnt lgkmcnt(0)
	s_barrier
	s_mov_b32 s8, 0
	v_readfirstlane_b32 s4, v14
	s_ashr_i32 s4, s4, 6
	s_mul_i32 s12, s4, s3
	s_add_i32 s12, s12, s2
	v_and_b32_e32 v5, 63, v14
	s_cmpk_gt_i32 s12, 0x3ff
	s_cbranch_scc1 .LBB0_1069
	s_load_dwordx2 s[4:5], s[0:1], 0xc0
	v_mov_b32_e32 v236, v5
	s_and_b32 s8, s12, 7
	s_lshr_b32 s9, s12, 3
	v_readfirstlane_b32 s10, v14
	s_lshr_b32 s10, s10, 6
	s_mul_i32 s10, s10, 0x4800
	s_add_i32 s10, s10, 0x2100
	s_lshl_b32 s11, s8, 15
	s_add_u32 s20, s44, 0xf350000
	s_addc_u32 s21, s45, 0
	s_add_u32 s20, s20, s11
	s_addc_u32 s21, s21, 0
	v_lshlrev_b32_e32 v229, 4, v236
	v_lshlrev_b32_e32 v230, 2, v236
	v_add_u32_e32 v231, s10, v229
	v_add_u32_e32 v230, s10, v230
	s_lshl_b32 s13, s9, 7
	v_lshlrev_b32_e32 v48, 1, v236
	v_add_u32_e32 v48, s13, v48
	v_add_u32_e32 v49, 0x4000, v48
	v_add_u32_e32 v50, 0x8000, v48
	v_add_u32_e32 v51, 0xc000, v48
	v_add_u32_e32 v52, 0x10000, v48
	v_add_u32_e32 v53, 0x14000, v48
	v_add_u32_e32 v54, 0x18000, v48
	v_add_u32_e32 v55, 0x1c000, v48
	v_add_u32_e32 v56, 0x20000, v48
	v_add_u32_e32 v57, 0x24000, v48
	v_add_u32_e32 v58, 0x28000, v48
	v_add_u32_e32 v59, 0x2c000, v48
	v_add_u32_e32 v60, 0x30000, v48
	v_add_u32_e32 v61, 0x34000, v48
	v_add_u32_e32 v62, 0x38000, v48
	v_add_u32_e32 v63, 0x3c000, v48
	s_lshr_b32 s13, s9, 5
	s_lshl_b32 s13, s13, 2
	v_lshrrev_b32_e32 v64, 4, v236
	v_add_u32_e32 v64, s13, v64
	v_bfe_u32 v65, v236, 3, 1
	v_lshl_add_u32 v64, v64, 1, v65
	s_and_b32 s13, s9, 31
	v_lshlrev_b32_e32 v64, 5, v64
	v_add_u32_e32 v64, s13, v64
	v_and_b32_e32 v65, 7, v236
	v_lshl_add_u32 v64, v64, 3, v65
	v_lshlrev_b32_e32 v64, 1, v64
	v_add_u32_e32 v65, 0x4000, v64
	v_add_u32_e32 v66, 0x8000, v64
	v_add_u32_e32 v67, 0xc000, v64
	v_add_u32_e32 v68, 0x10000, v64
	v_add_u32_e32 v69, 0x14000, v64
	v_add_u32_e32 v70, 0x18000, v64
	v_add_u32_e32 v71, 0x1c000, v64
	v_add_u32_e32 v72, 0x20000, v64
	v_add_u32_e32 v73, 0x24000, v64
	v_add_u32_e32 v74, 0x28000, v64
	v_add_u32_e32 v75, 0x2c000, v64
	v_add_u32_e32 v76, 0x30000, v64
	v_add_u32_e32 v77, 0x34000, v64
	v_add_u32_e32 v78, 0x38000, v64
	v_add_u32_e32 v79, 0x3c000, v64
	v_mov_b32_e32 v228, 0
	s_waitcnt lgkmcnt(0)
	s_lshl_b32 s11, s8, 21
	s_add_u32 s16, s4, s11
	s_addc_u32 s17, s5, 0
	s_add_u32 s18, s16, 0x2000000
	s_addc_u32 s19, s17, 0
	global_load_dwordx4 v[96:99], v229, s[20:21]
	global_load_dwordx4 v[100:103], v229, s[20:21] offset:1024
	global_load_dwordx4 v[104:107], v229, s[20:21] offset:2048
	global_load_dwordx4 v[108:111], v229, s[20:21] offset:3072
	v_add_u32_e32 v232, 0x1000, v229
	global_load_dwordx4 v[112:115], v232, s[20:21]
	v_add_u32_e32 v233, 0x1400, v229
	global_load_dwordx4 v[116:119], v233, s[20:21]
	v_add_u32_e32 v234, 0x1800, v229
	global_load_dwordx4 v[120:123], v234, s[20:21]
	v_add_u32_e32 v235, 0x1c00, v229
	global_load_dwordx4 v[124:127], v235, s[20:21]
	v_add_u32_e32 v232, 0x2000, v229
	global_load_dwordx4 v[128:131], v232, s[20:21]
	v_add_u32_e32 v233, 0x2400, v229
	global_load_dwordx4 v[132:135], v233, s[20:21]
	v_add_u32_e32 v234, 0x2800, v229
	global_load_dwordx4 v[136:139], v234, s[20:21]
	v_add_u32_e32 v235, 0x2c00, v229
	global_load_dwordx4 v[140:143], v235, s[20:21]
	v_add_u32_e32 v232, 0x3000, v229
	global_load_dwordx4 v[144:147], v232, s[20:21]
	v_add_u32_e32 v233, 0x3400, v229
	global_load_dwordx4 v[148:151], v233, s[20:21]
	v_add_u32_e32 v234, 0x3800, v229
	global_load_dwordx4 v[152:155], v234, s[20:21]
	v_add_u32_e32 v235, 0x3c00, v229
	global_load_dwordx4 v[156:159], v235, s[20:21]
	global_load_ushort v0, v48, s[16:17]
	global_load_ushort v1, v49, s[16:17]
	global_load_ushort v2, v50, s[16:17]
	global_load_ushort v3, v51, s[16:17]
	global_load_ushort v4, v52, s[16:17]
	global_load_ushort v5, v53, s[16:17]
	global_load_ushort v6, v54, s[16:17]
	global_load_ushort v7, v55, s[16:17]
	global_load_ushort v8, v56, s[16:17]
	global_load_ushort v9, v57, s[16:17]
	global_load_ushort v10, v58, s[16:17]
	global_load_ushort v11, v59, s[16:17]
	global_load_ushort v12, v60, s[16:17]
	global_load_ushort v13, v61, s[16:17]
	global_load_ushort v14, v62, s[16:17]
	global_load_ushort v15, v63, s[16:17]
	s_add_u32 s16, s16, 0x40000
	s_addc_u32 s17, s17, 0
	global_load_ushort v16, v48, s[16:17]
	global_load_ushort v17, v49, s[16:17]
	global_load_ushort v18, v50, s[16:17]
	global_load_ushort v19, v51, s[16:17]
	global_load_ushort v20, v52, s[16:17]
	global_load_ushort v21, v53, s[16:17]
	global_load_ushort v22, v54, s[16:17]
	global_load_ushort v23, v55, s[16:17]
	global_load_ushort v24, v56, s[16:17]
	global_load_ushort v25, v57, s[16:17]
	global_load_ushort v26, v58, s[16:17]
	global_load_ushort v27, v59, s[16:17]
	global_load_ushort v28, v60, s[16:17]
	global_load_ushort v29, v61, s[16:17]
	global_load_ushort v30, v62, s[16:17]
	global_load_ushort v31, v63, s[16:17]
	s_add_u32 s16, s16, 0x40000
	s_addc_u32 s17, s17, 0
	s_waitcnt vmcnt(32)
	ds_write_b128 v231, v[96:99]
	ds_write_b128 v231, v[100:103] offset:1024
	ds_write_b128 v231, v[104:107] offset:2048
	ds_write_b128 v231, v[108:111] offset:3072
	ds_write_b128 v231, v[112:115] offset:4096
	ds_write_b128 v231, v[116:119] offset:5120
	ds_write_b128 v231, v[120:123] offset:6144
	ds_write_b128 v231, v[124:127] offset:7168
	ds_write_b128 v231, v[128:131] offset:8192
	ds_write_b128 v231, v[132:135] offset:9216
	ds_write_b128 v231, v[136:139] offset:10240
	ds_write_b128 v231, v[140:143] offset:11264
	ds_write_b128 v231, v[144:147] offset:12288
	ds_write_b128 v231, v[148:151] offset:13312
	ds_write_b128 v231, v[152:155] offset:14336
	ds_write_b128 v231, v[156:159] offset:15360
	s_waitcnt lgkmcnt(0)
; DI bf16_t f2bf(float a) { return (bf16_t)(pk2(a, 0.f) & 0xffffu); }
; DI float bf2f(bf16_t v) { return __uint_as_float(((unsigned)v) << 16); }
; DI void p3_scan(const Params& p) {
;     ...
;         for (int c0 = 0; c0 < 128; c0 += 32) {
;             float v[32], d[32];
; #pragma unroll
;             for (int j = 0; j < 32; ++j) { v[j] = bf2f(sl[(size_t)(c0 + j) * 8192]); d[j] = dc[(c0 + j) * 64]; }
;             __builtin_amdgcn_sched_barrier(0);
; #pragma unroll
;             for (int j = 0; j < 32; ++j) { sp[(size_t)(c0 + j) * 8192] = f2bf(S); S = S * d[j] + v[j]; }
	ds_read_b32 v96, v230
	ds_read_b32 v97, v230 offset:256
	ds_read_b32 v98, v230 offset:512
	ds_read_b32 v99, v230 offset:768
	ds_read_b32 v100, v230 offset:1024
	ds_read_b32 v101, v230 offset:1280
	ds_read_b32 v102, v230 offset:1536
	ds_read_b32 v103, v230 offset:1792
	ds_read_b32 v104, v230 offset:2048
	ds_read_b32 v105, v230 offset:2304
	ds_read_b32 v106, v230 offset:2560
	ds_read_b32 v107, v230 offset:2816
	ds_read_b32 v108, v230 offset:3072
	ds_read_b32 v109, v230 offset:3328
	ds_read_b32 v110, v230 offset:3584
	ds_read_b32 v111, v230 offset:3840
	ds_read_b32 v112, v230 offset:4096
	ds_read_b32 v113, v230 offset:4352
	ds_read_b32 v114, v230 offset:4608
	ds_read_b32 v115, v230 offset:4864
	ds_read_b32 v116, v230 offset:5120
	ds_read_b32 v117, v230 offset:5376
	ds_read_b32 v118, v230 offset:5632
	ds_read_b32 v119, v230 offset:5888
	ds_read_b32 v120, v230 offset:6144
	ds_read_b32 v121, v230 offset:6400
	ds_read_b32 v122, v230 offset:6656
	ds_read_b32 v123, v230 offset:6912
	ds_read_b32 v124, v230 offset:7168
	ds_read_b32 v125, v230 offset:7424
	ds_read_b32 v126, v230 offset:7680
	ds_read_b32 v127, v230 offset:7936
	ds_read_b32 v128, v230 offset:8192
	ds_read_b32 v129, v230 offset:8448
	ds_read_b32 v130, v230 offset:8704
	ds_read_b32 v131, v230 offset:8960
	ds_read_b32 v132, v230 offset:9216
	ds_read_b32 v133, v230 offset:9472
	ds_read_b32 v134, v230 offset:9728
	ds_read_b32 v135, v230 offset:9984
	ds_read_b32 v136, v230 offset:10240
	ds_read_b32 v137, v230 offset:10496
	ds_read_b32 v138, v230 offset:10752
	ds_read_b32 v139, v230 offset:11008
	ds_read_b32 v140, v230 offset:11264
	ds_read_b32 v141, v230 offset:11520
	ds_read_b32 v142, v230 offset:11776
	ds_read_b32 v143, v230 offset:12032
	ds_read_b32 v144, v230 offset:12288
	ds_read_b32 v145, v230 offset:12544
	ds_read_b32 v146, v230 offset:12800
	ds_read_b32 v147, v230 offset:13056
	ds_read_b32 v148, v230 offset:13312
	ds_read_b32 v149, v230 offset:13568
	ds_read_b32 v150, v230 offset:13824
	ds_read_b32 v151, v230 offset:14080
	ds_read_b32 v152, v230 offset:14336
	ds_read_b32 v153, v230 offset:14592
	ds_read_b32 v154, v230 offset:14848
	ds_read_b32 v155, v230 offset:15104
	ds_read_b32 v156, v230 offset:15360
	ds_read_b32 v157, v230 offset:15616
	ds_read_b32 v158, v230 offset:15872
	ds_read_b32 v159, v230 offset:16128
	s_waitcnt lgkmcnt(0)
	v_add_u32_e32 v232, 0x4000, v229
	global_load_dwordx4 v[160:163], v232, s[20:21]
	v_add_u32_e32 v233, 0x4400, v229
	global_load_dwordx4 v[164:167], v233, s[20:21]
	v_add_u32_e32 v234, 0x4800, v229
	global_load_dwordx4 v[168:171], v234, s[20:21]
	v_add_u32_e32 v235, 0x4c00, v229
	global_load_dwordx4 v[172:175], v235, s[20:21]
	v_add_u32_e32 v232, 0x5000, v229
	global_load_dwordx4 v[176:179], v232, s[20:21]
	v_add_u32_e32 v233, 0x5400, v229
	global_load_dwordx4 v[180:183], v233, s[20:21]
	v_add_u32_e32 v234, 0x5800, v229
	global_load_dwordx4 v[190:193], v234, s[20:21]
	v_add_u32_e32 v235, 0x5c00, v229
	global_load_dwordx4 v[194:197], v235, s[20:21]
	v_add_u32_e32 v232, 0x6000, v229
	global_load_dwordx4 v[204:207], v232, s[20:21]
	v_add_u32_e32 v233, 0x6400, v229
	global_load_dwordx4 v[208:211], v233, s[20:21]
	v_add_u32_e32 v234, 0x6800, v229
	global_load_dwordx4 v[212:215], v234, s[20:21]
	v_add_u32_e32 v235, 0x6c00, v229
	global_load_dwordx4 v[216:219], v235, s[20:21]
	v_add_u32_e32 v232, 0x7000, v229
	global_load_dwordx4 v[220:223], v232, s[20:21]
	v_add_u32_e32 v233, 0x7400, v229
	global_load_dwordx4 v[224:227], v233, s[20:21]
	v_add_u32_e32 v234, 0x7800, v229
	global_load_dwordx4 v[238:241], v234, s[20:21]
	v_add_u32_e32 v235, 0x7c00, v229
	global_load_dwordx4 v[242:245], v235, s[20:21]
	s_waitcnt vmcnt(32)
	global_load_ushort v32, v48, s[16:17]
	global_load_ushort v33, v49, s[16:17]
	global_load_ushort v34, v50, s[16:17]
	global_load_ushort v35, v51, s[16:17]
	global_load_ushort v36, v52, s[16:17]
	global_load_ushort v37, v53, s[16:17]
	global_load_ushort v38, v54, s[16:17]
	global_load_ushort v39, v55, s[16:17]
	global_load_ushort v40, v56, s[16:17]
	global_load_ushort v41, v57, s[16:17]
	global_load_ushort v42, v58, s[16:17]
	global_load_ushort v43, v59, s[16:17]
	global_load_ushort v44, v60, s[16:17]
	global_load_ushort v45, v61, s[16:17]
	global_load_ushort v46, v62, s[16:17]
	global_load_ushort v47, v63, s[16:17]
	s_add_u32 s16, s16, 0x40000
	s_addc_u32 s17, s17, 0
	v_lshlrev_b32_e32 v0, 16, v0
	v_cvt_pk_bf16_f32 v80, v228, v228
	global_store_short v64, v80, s[18:19]
	v_fma_f32 v228, v228, v96, v0
	v_lshlrev_b32_e32 v1, 16, v1
	v_cvt_pk_bf16_f32 v81, v228, v228
	global_store_short v65, v81, s[18:19]
	v_fma_f32 v228, v228, v97, v1
	v_lshlrev_b32_e32 v2, 16, v2
	v_cvt_pk_bf16_f32 v82, v228, v228
	global_store_short v66, v82, s[18:19]
	v_fma_f32 v228, v228, v98, v2
	v_lshlrev_b32_e32 v3, 16, v3
	v_cvt_pk_bf16_f32 v83, v228, v228
	global_store_short v67, v83, s[18:19]
	v_fma_f32 v228, v228, v99, v3
	v_lshlrev_b32_e32 v4, 16, v4
	v_cvt_pk_bf16_f32 v84, v228, v228
	global_store_short v68, v84, s[18:19]
	v_fma_f32 v228, v228, v100, v4
	v_lshlrev_b32_e32 v5, 16, v5
	v_cvt_pk_bf16_f32 v85, v228, v228
	global_store_short v69, v85, s[18:19]
	v_fma_f32 v228, v228, v101, v5
	v_lshlrev_b32_e32 v6, 16, v6
	v_cvt_pk_bf16_f32 v86, v228, v228
	global_store_short v70, v86, s[18:19]
	v_fma_f32 v228, v228, v102, v6
	v_lshlrev_b32_e32 v7, 16, v7
	v_cvt_pk_bf16_f32 v87, v228, v228
	global_store_short v71, v87, s[18:19]
	v_fma_f32 v228, v228, v103, v7
	v_lshlrev_b32_e32 v8, 16, v8
	v_cvt_pk_bf16_f32 v88, v228, v228
	global_store_short v72, v88, s[18:19]
	v_fma_f32 v228, v228, v104, v8
	v_lshlrev_b32_e32 v9, 16, v9
	v_cvt_pk_bf16_f32 v89, v228, v228
	global_store_short v73, v89, s[18:19]
	v_fma_f32 v228, v228, v105, v9
	v_lshlrev_b32_e32 v10, 16, v10
	v_cvt_pk_bf16_f32 v90, v228, v228
	global_store_short v74, v90, s[18:19]
	v_fma_f32 v228, v228, v106, v10
	v_lshlrev_b32_e32 v11, 16, v11
	v_cvt_pk_bf16_f32 v91, v228, v228
	global_store_short v75, v91, s[18:19]
	v_fma_f32 v228, v228, v107, v11
	v_lshlrev_b32_e32 v12, 16, v12
	v_cvt_pk_bf16_f32 v92, v228, v228
	global_store_short v76, v92, s[18:19]
	v_fma_f32 v228, v228, v108, v12
	v_lshlrev_b32_e32 v13, 16, v13
	v_cvt_pk_bf16_f32 v93, v228, v228
	global_store_short v77, v93, s[18:19]
	v_fma_f32 v228, v228, v109, v13
	v_lshlrev_b32_e32 v14, 16, v14
	v_cvt_pk_bf16_f32 v94, v228, v228
	global_store_short v78, v94, s[18:19]
	v_fma_f32 v228, v228, v110, v14
	v_lshlrev_b32_e32 v15, 16, v15
	v_cvt_pk_bf16_f32 v95, v228, v228
	global_store_short v79, v95, s[18:19]
	v_fma_f32 v228, v228, v111, v15
	s_add_u32 s18, s18, 0x40000
	s_addc_u32 s19, s19, 0
	s_waitcnt vmcnt(48)
; DI bf16_t f2bf(float a) { return (bf16_t)(pk2(a, 0.f) & 0xffffu); }
; DI float bf2f(bf16_t v) { return __uint_as_float(((unsigned)v) << 16); }
; DI void p3_scan(const Params& p) {
;     ...
;         for (int c0 = 0; c0 < 128; c0 += 32) {
;             float v[32], d[32];
; #pragma unroll
;             for (int j = 0; j < 32; ++j) { v[j] = bf2f(sl[(size_t)(c0 + j) * 8192]); d[j] = dc[(c0 + j) * 64]; }
;             __builtin_amdgcn_sched_barrier(0);
; #pragma unroll
;             for (int j = 0; j < 32; ++j) { sp[(size_t)(c0 + j) * 8192] = f2bf(S); S = S * d[j] + v[j]; }
	global_load_ushort v0, v48, s[16:17]
	global_load_ushort v1, v49, s[16:17]
	global_load_ushort v2, v50, s[16:17]
	global_load_ushort v3, v51, s[16:17]
	global_load_ushort v4, v52, s[16:17]
	global_load_ushort v5, v53, s[16:17]
	global_load_ushort v6, v54, s[16:17]
	global_load_ushort v7, v55, s[16:17]
	global_load_ushort v8, v56, s[16:17]
	global_load_ushort v9, v57, s[16:17]
	global_load_ushort v10, v58, s[16:17]
	global_load_ushort v11, v59, s[16:17]
	global_load_ushort v12, v60, s[16:17]
	global_load_ushort v13, v61, s[16:17]
	global_load_ushort v14, v62, s[16:17]
	global_load_ushort v15, v63, s[16:17]
	s_add_u32 s16, s16, 0x40000
	s_addc_u32 s17, s17, 0
	v_lshlrev_b32_e32 v16, 16, v16
	v_cvt_pk_bf16_f32 v80, v228, v228
	global_store_short v64, v80, s[18:19]
	v_fma_f32 v228, v228, v112, v16
	v_lshlrev_b32_e32 v17, 16, v17
	v_cvt_pk_bf16_f32 v81, v228, v228
	global_store_short v65, v81, s[18:19]
	v_fma_f32 v228, v228, v113, v17
	v_lshlrev_b32_e32 v18, 16, v18
	v_cvt_pk_bf16_f32 v82, v228, v228
	global_store_short v66, v82, s[18:19]
	v_fma_f32 v228, v228, v114, v18
	v_lshlrev_b32_e32 v19, 16, v19
	v_cvt_pk_bf16_f32 v83, v228, v228
	global_store_short v67, v83, s[18:19]
	v_fma_f32 v228, v228, v115, v19
	v_lshlrev_b32_e32 v20, 16, v20
	v_cvt_pk_bf16_f32 v84, v228, v228
	global_store_short v68, v84, s[18:19]
	v_fma_f32 v228, v228, v116, v20
	v_lshlrev_b32_e32 v21, 16, v21
	v_cvt_pk_bf16_f32 v85, v228, v228
	global_store_short v69, v85, s[18:19]
	v_fma_f32 v228, v228, v117, v21
	v_lshlrev_b32_e32 v22, 16, v22
	v_cvt_pk_bf16_f32 v86, v228, v228
	global_store_short v70, v86, s[18:19]
	v_fma_f32 v228, v228, v118, v22
	v_lshlrev_b32_e32 v23, 16, v23
	v_cvt_pk_bf16_f32 v87, v228, v228
	global_store_short v71, v87, s[18:19]
	v_fma_f32 v228, v228, v119, v23
	v_lshlrev_b32_e32 v24, 16, v24
	v_cvt_pk_bf16_f32 v88, v228, v228
	global_store_short v72, v88, s[18:19]
	v_fma_f32 v228, v228, v120, v24
	v_lshlrev_b32_e32 v25, 16, v25
	v_cvt_pk_bf16_f32 v89, v228, v228
	global_store_short v73, v89, s[18:19]
	v_fma_f32 v228, v228, v121, v25
	v_lshlrev_b32_e32 v26, 16, v26
	v_cvt_pk_bf16_f32 v90, v228, v228
	global_store_short v74, v90, s[18:19]
	v_fma_f32 v228, v228, v122, v26
	v_lshlrev_b32_e32 v27, 16, v27
	v_cvt_pk_bf16_f32 v91, v228, v228
	global_store_short v75, v91, s[18:19]
	v_fma_f32 v228, v228, v123, v27
	v_lshlrev_b32_e32 v28, 16, v28
	v_cvt_pk_bf16_f32 v92, v228, v228
	global_store_short v76, v92, s[18:19]
	v_fma_f32 v228, v228, v124, v28
	v_lshlrev_b32_e32 v29, 16, v29
	v_cvt_pk_bf16_f32 v93, v228, v228
	global_store_short v77, v93, s[18:19]
	v_fma_f32 v228, v228, v125, v29
	v_lshlrev_b32_e32 v30, 16, v30
	v_cvt_pk_bf16_f32 v94, v228, v228
	global_store_short v78, v94, s[18:19]
	v_fma_f32 v228, v228, v126, v30
	v_lshlrev_b32_e32 v31, 16, v31
	v_cvt_pk_bf16_f32 v95, v228, v228
	global_store_short v79, v95, s[18:19]
	v_fma_f32 v228, v228, v127, v31
	s_add_u32 s18, s18, 0x40000
	s_addc_u32 s19, s19, 0
	s_waitcnt vmcnt(48)
	global_load_ushort v16, v48, s[16:17]
	global_load_ushort v17, v49, s[16:17]
	global_load_ushort v18, v50, s[16:17]
	global_load_ushort v19, v51, s[16:17]
	global_load_ushort v20, v52, s[16:17]
	global_load_ushort v21, v53, s[16:17]
	global_load_ushort v22, v54, s[16:17]
	global_load_ushort v23, v55, s[16:17]
	global_load_ushort v24, v56, s[16:17]
	global_load_ushort v25, v57, s[16:17]
	global_load_ushort v26, v58, s[16:17]
	global_load_ushort v27, v59, s[16:17]
	global_load_ushort v28, v60, s[16:17]
	global_load_ushort v29, v61, s[16:17]
	global_load_ushort v30, v62, s[16:17]
	global_load_ushort v31, v63, s[16:17]
	s_add_u32 s16, s16, 0x40000
	s_addc_u32 s17, s17, 0
	v_lshlrev_b32_e32 v32, 16, v32
	v_cvt_pk_bf16_f32 v80, v228, v228
	global_store_short v64, v80, s[18:19]
	v_fma_f32 v228, v228, v128, v32
	v_lshlrev_b32_e32 v33, 16, v33
	v_cvt_pk_bf16_f32 v81, v228, v228
	global_store_short v65, v81, s[18:19]
	v_fma_f32 v228, v228, v129, v33
	v_lshlrev_b32_e32 v34, 16, v34
	v_cvt_pk_bf16_f32 v82, v228, v228
	global_store_short v66, v82, s[18:19]
	v_fma_f32 v228, v228, v130, v34
	v_lshlrev_b32_e32 v35, 16, v35
	v_cvt_pk_bf16_f32 v83, v228, v228
	global_store_short v67, v83, s[18:19]
	v_fma_f32 v228, v228, v131, v35
	v_lshlrev_b32_e32 v36, 16, v36
	v_cvt_pk_bf16_f32 v84, v228, v228
	global_store_short v68, v84, s[18:19]
	v_fma_f32 v228, v228, v132, v36
	v_lshlrev_b32_e32 v37, 16, v37
	v_cvt_pk_bf16_f32 v85, v228, v228
	global_store_short v69, v85, s[18:19]
	v_fma_f32 v228, v228, v133, v37
	v_lshlrev_b32_e32 v38, 16, v38
	v_cvt_pk_bf16_f32 v86, v228, v228
	global_store_short v70, v86, s[18:19]
	v_fma_f32 v228, v228, v134, v38
	v_lshlrev_b32_e32 v39, 16, v39
	v_cvt_pk_bf16_f32 v87, v228, v228
	global_store_short v71, v87, s[18:19]
	v_fma_f32 v228, v228, v135, v39
	v_lshlrev_b32_e32 v40, 16, v40
	v_cvt_pk_bf16_f32 v88, v228, v228
	global_store_short v72, v88, s[18:19]
	v_fma_f32 v228, v228, v136, v40
	v_lshlrev_b32_e32 v41, 16, v41
	v_cvt_pk_bf16_f32 v89, v228, v228
	global_store_short v73, v89, s[18:19]
	v_fma_f32 v228, v228, v137, v41
	v_lshlrev_b32_e32 v42, 16, v42
	v_cvt_pk_bf16_f32 v90, v228, v228
	global_store_short v74, v90, s[18:19]
	v_fma_f32 v228, v228, v138, v42
	v_lshlrev_b32_e32 v43, 16, v43
	v_cvt_pk_bf16_f32 v91, v228, v228
	global_store_short v75, v91, s[18:19]
	v_fma_f32 v228, v228, v139, v43
	v_lshlrev_b32_e32 v44, 16, v44
	v_cvt_pk_bf16_f32 v92, v228, v228
	global_store_short v76, v92, s[18:19]
	v_fma_f32 v228, v228, v140, v44
	v_lshlrev_b32_e32 v45, 16, v45
	v_cvt_pk_bf16_f32 v93, v228, v228
	global_store_short v77, v93, s[18:19]
	v_fma_f32 v228, v228, v141, v45
	v_lshlrev_b32_e32 v46, 16, v46
	v_cvt_pk_bf16_f32 v94, v228, v228
	global_store_short v78, v94, s[18:19]
	v_fma_f32 v228, v228, v142, v46
	v_lshlrev_b32_e32 v47, 16, v47
	v_cvt_pk_bf16_f32 v95, v228, v228
	global_store_short v79, v95, s[18:19]
	v_fma_f32 v228, v228, v143, v47
	s_add_u32 s18, s18, 0x40000
	s_addc_u32 s19, s19, 0
	s_waitcnt vmcnt(48)
; DI bf16_t f2bf(float a) { return (bf16_t)(pk2(a, 0.f) & 0xffffu); }
; DI float bf2f(bf16_t v) { return __uint_as_float(((unsigned)v) << 16); }
; DI void p3_scan(const Params& p) {
;     ...
;         for (int c0 = 0; c0 < 128; c0 += 32) {
;             float v[32], d[32];
; #pragma unroll
;             for (int j = 0; j < 32; ++j) { v[j] = bf2f(sl[(size_t)(c0 + j) * 8192]); d[j] = dc[(c0 + j) * 64]; }
;             __builtin_amdgcn_sched_barrier(0);
; #pragma unroll
;             for (int j = 0; j < 32; ++j) { sp[(size_t)(c0 + j) * 8192] = f2bf(S); S = S * d[j] + v[j]; }
	global_load_ushort v32, v48, s[16:17]
	global_load_ushort v33, v49, s[16:17]
	global_load_ushort v34, v50, s[16:17]
	global_load_ushort v35, v51, s[16:17]
	global_load_ushort v36, v52, s[16:17]
	global_load_ushort v37, v53, s[16:17]
	global_load_ushort v38, v54, s[16:17]
	global_load_ushort v39, v55, s[16:17]
	global_load_ushort v40, v56, s[16:17]
	global_load_ushort v41, v57, s[16:17]
	global_load_ushort v42, v58, s[16:17]
	global_load_ushort v43, v59, s[16:17]
	global_load_ushort v44, v60, s[16:17]
	global_load_ushort v45, v61, s[16:17]
	global_load_ushort v46, v62, s[16:17]
	global_load_ushort v47, v63, s[16:17]
	s_add_u32 s16, s16, 0x40000
	s_addc_u32 s17, s17, 0
	v_lshlrev_b32_e32 v0, 16, v0
	v_cvt_pk_bf16_f32 v80, v228, v228
	global_store_short v64, v80, s[18:19]
	v_fma_f32 v228, v228, v144, v0
	v_lshlrev_b32_e32 v1, 16, v1
	v_cvt_pk_bf16_f32 v81, v228, v228
	global_store_short v65, v81, s[18:19]
	v_fma_f32 v228, v228, v145, v1
	v_lshlrev_b32_e32 v2, 16, v2
	v_cvt_pk_bf16_f32 v82, v228, v228
	global_store_short v66, v82, s[18:19]
	v_fma_f32 v228, v228, v146, v2
	v_lshlrev_b32_e32 v3, 16, v3
	v_cvt_pk_bf16_f32 v83, v228, v228
	global_store_short v67, v83, s[18:19]
	v_fma_f32 v228, v228, v147, v3
	v_lshlrev_b32_e32 v4, 16, v4
	v_cvt_pk_bf16_f32 v84, v228, v228
	global_store_short v68, v84, s[18:19]
	v_fma_f32 v228, v228, v148, v4
	v_lshlrev_b32_e32 v5, 16, v5
	v_cvt_pk_bf16_f32 v85, v228, v228
	global_store_short v69, v85, s[18:19]
	v_fma_f32 v228, v228, v149, v5
	v_lshlrev_b32_e32 v6, 16, v6
	v_cvt_pk_bf16_f32 v86, v228, v228
	global_store_short v70, v86, s[18:19]
	v_fma_f32 v228, v228, v150, v6
	v_lshlrev_b32_e32 v7, 16, v7
	v_cvt_pk_bf16_f32 v87, v228, v228
	global_store_short v71, v87, s[18:19]
	v_fma_f32 v228, v228, v151, v7
	v_lshlrev_b32_e32 v8, 16, v8
	v_cvt_pk_bf16_f32 v88, v228, v228
	global_store_short v72, v88, s[18:19]
	v_fma_f32 v228, v228, v152, v8
	v_lshlrev_b32_e32 v9, 16, v9
	v_cvt_pk_bf16_f32 v89, v228, v228
	global_store_short v73, v89, s[18:19]
	v_fma_f32 v228, v228, v153, v9
	v_lshlrev_b32_e32 v10, 16, v10
	v_cvt_pk_bf16_f32 v90, v228, v228
	global_store_short v74, v90, s[18:19]
	v_fma_f32 v228, v228, v154, v10
	v_lshlrev_b32_e32 v11, 16, v11
	v_cvt_pk_bf16_f32 v91, v228, v228
	global_store_short v75, v91, s[18:19]
	v_fma_f32 v228, v228, v155, v11
	v_lshlrev_b32_e32 v12, 16, v12
	v_cvt_pk_bf16_f32 v92, v228, v228
	global_store_short v76, v92, s[18:19]
	v_fma_f32 v228, v228, v156, v12
	v_lshlrev_b32_e32 v13, 16, v13
	v_cvt_pk_bf16_f32 v93, v228, v228
	global_store_short v77, v93, s[18:19]
	v_fma_f32 v228, v228, v157, v13
	v_lshlrev_b32_e32 v14, 16, v14
	v_cvt_pk_bf16_f32 v94, v228, v228
	global_store_short v78, v94, s[18:19]
	v_fma_f32 v228, v228, v158, v14
	v_lshlrev_b32_e32 v15, 16, v15
	v_cvt_pk_bf16_f32 v95, v228, v228
	global_store_short v79, v95, s[18:19]
	v_fma_f32 v228, v228, v159, v15
	s_add_u32 s18, s18, 0x40000
	s_addc_u32 s19, s19, 0
	ds_write_b128 v231, v[160:163]
	ds_write_b128 v231, v[164:167] offset:1024
	ds_write_b128 v231, v[168:171] offset:2048
	ds_write_b128 v231, v[172:175] offset:3072
	ds_write_b128 v231, v[176:179] offset:4096
	ds_write_b128 v231, v[180:183] offset:5120
	ds_write_b128 v231, v[190:193] offset:6144
	ds_write_b128 v231, v[194:197] offset:7168
	ds_write_b128 v231, v[204:207] offset:8192
	ds_write_b128 v231, v[208:211] offset:9216
	ds_write_b128 v231, v[212:215] offset:10240
	ds_write_b128 v231, v[216:219] offset:11264
	ds_write_b128 v231, v[220:223] offset:12288
	ds_write_b128 v231, v[224:227] offset:13312
	ds_write_b128 v231, v[238:241] offset:14336
	ds_write_b128 v231, v[242:245] offset:15360
	s_waitcnt lgkmcnt(0)
	ds_read_b32 v160, v230
	ds_read_b32 v161, v230 offset:256
	ds_read_b32 v162, v230 offset:512
	ds_read_b32 v163, v230 offset:768
	ds_read_b32 v164, v230 offset:1024
	ds_read_b32 v165, v230 offset:1280
	ds_read_b32 v166, v230 offset:1536
	ds_read_b32 v167, v230 offset:1792
	ds_read_b32 v168, v230 offset:2048
	ds_read_b32 v169, v230 offset:2304
	ds_read_b32 v170, v230 offset:2560
	ds_read_b32 v171, v230 offset:2816
	ds_read_b32 v172, v230 offset:3072
	ds_read_b32 v173, v230 offset:3328
	ds_read_b32 v174, v230 offset:3584
	ds_read_b32 v175, v230 offset:3840
	ds_read_b32 v176, v230 offset:4096
	ds_read_b32 v177, v230 offset:4352
	ds_read_b32 v178, v230 offset:4608
	ds_read_b32 v179, v230 offset:4864
	ds_read_b32 v180, v230 offset:5120
	ds_read_b32 v181, v230 offset:5376
	ds_read_b32 v182, v230 offset:5632
	ds_read_b32 v183, v230 offset:5888
	ds_read_b32 v190, v230 offset:6144
	ds_read_b32 v191, v230 offset:6400
	ds_read_b32 v192, v230 offset:6656
	ds_read_b32 v193, v230 offset:6912
	ds_read_b32 v194, v230 offset:7168
	ds_read_b32 v195, v230 offset:7424
	ds_read_b32 v196, v230 offset:7680
	ds_read_b32 v197, v230 offset:7936
	ds_read_b32 v204, v230 offset:8192
	ds_read_b32 v205, v230 offset:8448
	ds_read_b32 v206, v230 offset:8704
	ds_read_b32 v207, v230 offset:8960
	ds_read_b32 v208, v230 offset:9216
	ds_read_b32 v209, v230 offset:9472
	ds_read_b32 v210, v230 offset:9728
	ds_read_b32 v211, v230 offset:9984
	ds_read_b32 v212, v230 offset:10240
	ds_read_b32 v213, v230 offset:10496
	ds_read_b32 v214, v230 offset:10752
	ds_read_b32 v215, v230 offset:11008
	ds_read_b32 v216, v230 offset:11264
	ds_read_b32 v217, v230 offset:11520
	ds_read_b32 v218, v230 offset:11776
	ds_read_b32 v219, v230 offset:12032
	ds_read_b32 v220, v230 offset:12288
	ds_read_b32 v221, v230 offset:12544
	ds_read_b32 v222, v230 offset:12800
	ds_read_b32 v223, v230 offset:13056
	ds_read_b32 v224, v230 offset:13312
	ds_read_b32 v225, v230 offset:13568
	ds_read_b32 v226, v230 offset:13824
	ds_read_b32 v227, v230 offset:14080
	ds_read_b32 v238, v230 offset:14336
	ds_read_b32 v239, v230 offset:14592
	ds_read_b32 v240, v230 offset:14848
	ds_read_b32 v241, v230 offset:15104
	ds_read_b32 v242, v230 offset:15360
	ds_read_b32 v243, v230 offset:15616
	ds_read_b32 v244, v230 offset:15872
	ds_read_b32 v245, v230 offset:16128
	s_waitcnt lgkmcnt(0)
; DI bf16_t f2bf(float a) { return (bf16_t)(pk2(a, 0.f) & 0xffffu); }
; DI float bf2f(bf16_t v) { return __uint_as_float(((unsigned)v) << 16); }
; DI void p3_scan(const Params& p) {
;     ...
;         for (int c0 = 0; c0 < 128; c0 += 32) {
;             float v[32], d[32];
; #pragma unroll
;             for (int j = 0; j < 32; ++j) { v[j] = bf2f(sl[(size_t)(c0 + j) * 8192]); d[j] = dc[(c0 + j) * 64]; }
;             __builtin_amdgcn_sched_barrier(0);
; #pragma unroll
;             for (int j = 0; j < 32; ++j) { sp[(size_t)(c0 + j) * 8192] = f2bf(S); S = S * d[j] + v[j]; }
	s_waitcnt vmcnt(48)
	global_load_ushort v0, v48, s[16:17]
	global_load_ushort v1, v49, s[16:17]
	global_load_ushort v2, v50, s[16:17]
	global_load_ushort v3, v51, s[16:17]
	global_load_ushort v4, v52, s[16:17]
	global_load_ushort v5, v53, s[16:17]
	global_load_ushort v6, v54, s[16:17]
	global_load_ushort v7, v55, s[16:17]
	global_load_ushort v8, v56, s[16:17]
	global_load_ushort v9, v57, s[16:17]
	global_load_ushort v10, v58, s[16:17]
	global_load_ushort v11, v59, s[16:17]
	global_load_ushort v12, v60, s[16:17]
	global_load_ushort v13, v61, s[16:17]
	global_load_ushort v14, v62, s[16:17]
	global_load_ushort v15, v63, s[16:17]
	s_add_u32 s16, s16, 0x40000
	s_addc_u32 s17, s17, 0
	v_lshlrev_b32_e32 v16, 16, v16
	v_cvt_pk_bf16_f32 v80, v228, v228
	global_store_short v64, v80, s[18:19]
	v_fma_f32 v228, v228, v160, v16
	v_lshlrev_b32_e32 v17, 16, v17
	v_cvt_pk_bf16_f32 v81, v228, v228
	global_store_short v65, v81, s[18:19]
	v_fma_f32 v228, v228, v161, v17
	v_lshlrev_b32_e32 v18, 16, v18
	v_cvt_pk_bf16_f32 v82, v228, v228
	global_store_short v66, v82, s[18:19]
	v_fma_f32 v228, v228, v162, v18
	v_lshlrev_b32_e32 v19, 16, v19
	v_cvt_pk_bf16_f32 v83, v228, v228
	global_store_short v67, v83, s[18:19]
	v_fma_f32 v228, v228, v163, v19
	v_lshlrev_b32_e32 v20, 16, v20
	v_cvt_pk_bf16_f32 v84, v228, v228
	global_store_short v68, v84, s[18:19]
	v_fma_f32 v228, v228, v164, v20
	v_lshlrev_b32_e32 v21, 16, v21
	v_cvt_pk_bf16_f32 v85, v228, v228
	global_store_short v69, v85, s[18:19]
	v_fma_f32 v228, v228, v165, v21
	v_lshlrev_b32_e32 v22, 16, v22
	v_cvt_pk_bf16_f32 v86, v228, v228
	global_store_short v70, v86, s[18:19]
	v_fma_f32 v228, v228, v166, v22
	v_lshlrev_b32_e32 v23, 16, v23
	v_cvt_pk_bf16_f32 v87, v228, v228
	global_store_short v71, v87, s[18:19]
	v_fma_f32 v228, v228, v167, v23
	v_lshlrev_b32_e32 v24, 16, v24
	v_cvt_pk_bf16_f32 v88, v228, v228
	global_store_short v72, v88, s[18:19]
	v_fma_f32 v228, v228, v168, v24
	v_lshlrev_b32_e32 v25, 16, v25
	v_cvt_pk_bf16_f32 v89, v228, v228
	global_store_short v73, v89, s[18:19]
	v_fma_f32 v228, v228, v169, v25
	v_lshlrev_b32_e32 v26, 16, v26
	v_cvt_pk_bf16_f32 v90, v228, v228
	global_store_short v74, v90, s[18:19]
	v_fma_f32 v228, v228, v170, v26
	v_lshlrev_b32_e32 v27, 16, v27
	v_cvt_pk_bf16_f32 v91, v228, v228
	global_store_short v75, v91, s[18:19]
	v_fma_f32 v228, v228, v171, v27
	v_lshlrev_b32_e32 v28, 16, v28
	v_cvt_pk_bf16_f32 v92, v228, v228
	global_store_short v76, v92, s[18:19]
	v_fma_f32 v228, v228, v172, v28
	v_lshlrev_b32_e32 v29, 16, v29
	v_cvt_pk_bf16_f32 v93, v228, v228
	global_store_short v77, v93, s[18:19]
	v_fma_f32 v228, v228, v173, v29
	v_lshlrev_b32_e32 v30, 16, v30
	v_cvt_pk_bf16_f32 v94, v228, v228
	global_store_short v78, v94, s[18:19]
	v_fma_f32 v228, v228, v174, v30
	v_lshlrev_b32_e32 v31, 16, v31
	v_cvt_pk_bf16_f32 v95, v228, v228
	global_store_short v79, v95, s[18:19]
	v_fma_f32 v228, v228, v175, v31
	s_add_u32 s18, s18, 0x40000
	s_addc_u32 s19, s19, 0
	s_waitcnt vmcnt(48)
	global_load_ushort v16, v48, s[16:17]
	global_load_ushort v17, v49, s[16:17]
	global_load_ushort v18, v50, s[16:17]
	global_load_ushort v19, v51, s[16:17]
	global_load_ushort v20, v52, s[16:17]
	global_load_ushort v21, v53, s[16:17]
	global_load_ushort v22, v54, s[16:17]
	global_load_ushort v23, v55, s[16:17]
	global_load_ushort v24, v56, s[16:17]
	global_load_ushort v25, v57, s[16:17]
	global_load_ushort v26, v58, s[16:17]
	global_load_ushort v27, v59, s[16:17]
	global_load_ushort v28, v60, s[16:17]
	global_load_ushort v29, v61, s[16:17]
	global_load_ushort v30, v62, s[16:17]
	global_load_ushort v31, v63, s[16:17]
	s_add_u32 s16, s16, 0x40000
	s_addc_u32 s17, s17, 0
	v_lshlrev_b32_e32 v32, 16, v32
	v_cvt_pk_bf16_f32 v80, v228, v228
	global_store_short v64, v80, s[18:19]
	v_fma_f32 v228, v228, v176, v32
	v_lshlrev_b32_e32 v33, 16, v33
	v_cvt_pk_bf16_f32 v81, v228, v228
	global_store_short v65, v81, s[18:19]
	v_fma_f32 v228, v228, v177, v33
	v_lshlrev_b32_e32 v34, 16, v34
	v_cvt_pk_bf16_f32 v82, v228, v228
	global_store_short v66, v82, s[18:19]
	v_fma_f32 v228, v228, v178, v34
	v_lshlrev_b32_e32 v35, 16, v35
	v_cvt_pk_bf16_f32 v83, v228, v228
	global_store_short v67, v83, s[18:19]
	v_fma_f32 v228, v228, v179, v35
	v_lshlrev_b32_e32 v36, 16, v36
	v_cvt_pk_bf16_f32 v84, v228, v228
	global_store_short v68, v84, s[18:19]
	v_fma_f32 v228, v228, v180, v36
	v_lshlrev_b32_e32 v37, 16, v37
	v_cvt_pk_bf16_f32 v85, v228, v228
	global_store_short v69, v85, s[18:19]
	v_fma_f32 v228, v228, v181, v37
	v_lshlrev_b32_e32 v38, 16, v38
	v_cvt_pk_bf16_f32 v86, v228, v228
	global_store_short v70, v86, s[18:19]
	v_fma_f32 v228, v228, v182, v38
	v_lshlrev_b32_e32 v39, 16, v39
	v_cvt_pk_bf16_f32 v87, v228, v228
	global_store_short v71, v87, s[18:19]
	v_fma_f32 v228, v228, v183, v39
	v_lshlrev_b32_e32 v40, 16, v40
	v_cvt_pk_bf16_f32 v88, v228, v228
	global_store_short v72, v88, s[18:19]
	v_fma_f32 v228, v228, v190, v40
	v_lshlrev_b32_e32 v41, 16, v41
	v_cvt_pk_bf16_f32 v89, v228, v228
	global_store_short v73, v89, s[18:19]
	v_fma_f32 v228, v228, v191, v41
	v_lshlrev_b32_e32 v42, 16, v42
	v_cvt_pk_bf16_f32 v90, v228, v228
	global_store_short v74, v90, s[18:19]
	v_fma_f32 v228, v228, v192, v42
	v_lshlrev_b32_e32 v43, 16, v43
	v_cvt_pk_bf16_f32 v91, v228, v228
	global_store_short v75, v91, s[18:19]
	v_fma_f32 v228, v228, v193, v43
	v_lshlrev_b32_e32 v44, 16, v44
	v_cvt_pk_bf16_f32 v92, v228, v228
	global_store_short v76, v92, s[18:19]
	v_fma_f32 v228, v228, v194, v44
	v_lshlrev_b32_e32 v45, 16, v45
	v_cvt_pk_bf16_f32 v93, v228, v228
	global_store_short v77, v93, s[18:19]
	v_fma_f32 v228, v228, v195, v45
	v_lshlrev_b32_e32 v46, 16, v46
	v_cvt_pk_bf16_f32 v94, v228, v228
	global_store_short v78, v94, s[18:19]
	v_fma_f32 v228, v228, v196, v46
	v_lshlrev_b32_e32 v47, 16, v47
	v_cvt_pk_bf16_f32 v95, v228, v228
	global_store_short v79, v95, s[18:19]
	v_fma_f32 v228, v228, v197, v47
	s_add_u32 s18, s18, 0x40000
	s_addc_u32 s19, s19, 0
	s_waitcnt vmcnt(48)
; DI bf16_t f2bf(float a) { return (bf16_t)(pk2(a, 0.f) & 0xffffu); }
; DI float bf2f(bf16_t v) { return __uint_as_float(((unsigned)v) << 16); }
; DI void p3_scan(const Params& p) {
;     ...
;         for (int c0 = 0; c0 < 128; c0 += 32) {
;             float v[32], d[32];
; #pragma unroll
;             for (int j = 0; j < 32; ++j) { v[j] = bf2f(sl[(size_t)(c0 + j) * 8192]); d[j] = dc[(c0 + j) * 64]; }
;             __builtin_amdgcn_sched_barrier(0);
; #pragma unroll
;             for (int j = 0; j < 32; ++j) { sp[(size_t)(c0 + j) * 8192] = f2bf(S); S = S * d[j] + v[j]; }
;         }
;         p.out[O_GLP + (size_t)bh * 8192 + dk * 128 + dv] = S;
	v_lshlrev_b32_e32 v0, 16, v0
	v_cvt_pk_bf16_f32 v80, v228, v228
	global_store_short v64, v80, s[18:19]
	v_fma_f32 v228, v228, v204, v0
	v_lshlrev_b32_e32 v1, 16, v1
	v_cvt_pk_bf16_f32 v81, v228, v228
	global_store_short v65, v81, s[18:19]
	v_fma_f32 v228, v228, v205, v1
	v_lshlrev_b32_e32 v2, 16, v2
	v_cvt_pk_bf16_f32 v82, v228, v228
	global_store_short v66, v82, s[18:19]
	v_fma_f32 v228, v228, v206, v2
	v_lshlrev_b32_e32 v3, 16, v3
	v_cvt_pk_bf16_f32 v83, v228, v228
	global_store_short v67, v83, s[18:19]
	v_fma_f32 v228, v228, v207, v3
	v_lshlrev_b32_e32 v4, 16, v4
	v_cvt_pk_bf16_f32 v84, v228, v228
	global_store_short v68, v84, s[18:19]
	v_fma_f32 v228, v228, v208, v4
	v_lshlrev_b32_e32 v5, 16, v5
	v_cvt_pk_bf16_f32 v85, v228, v228
	global_store_short v69, v85, s[18:19]
	v_fma_f32 v228, v228, v209, v5
	v_lshlrev_b32_e32 v6, 16, v6
	v_cvt_pk_bf16_f32 v86, v228, v228
	global_store_short v70, v86, s[18:19]
	v_fma_f32 v228, v228, v210, v6
	v_lshlrev_b32_e32 v7, 16, v7
	v_cvt_pk_bf16_f32 v87, v228, v228
	global_store_short v71, v87, s[18:19]
	v_fma_f32 v228, v228, v211, v7
	v_lshlrev_b32_e32 v8, 16, v8
	v_cvt_pk_bf16_f32 v88, v228, v228
	global_store_short v72, v88, s[18:19]
	v_fma_f32 v228, v228, v212, v8
	v_lshlrev_b32_e32 v9, 16, v9
	v_cvt_pk_bf16_f32 v89, v228, v228
	global_store_short v73, v89, s[18:19]
	v_fma_f32 v228, v228, v213, v9
	v_lshlrev_b32_e32 v10, 16, v10
	v_cvt_pk_bf16_f32 v90, v228, v228
	global_store_short v74, v90, s[18:19]
	v_fma_f32 v228, v228, v214, v10
	v_lshlrev_b32_e32 v11, 16, v11
	v_cvt_pk_bf16_f32 v91, v228, v228
	global_store_short v75, v91, s[18:19]
	v_fma_f32 v228, v228, v215, v11
	v_lshlrev_b32_e32 v12, 16, v12
	v_cvt_pk_bf16_f32 v92, v228, v228
	global_store_short v76, v92, s[18:19]
	v_fma_f32 v228, v228, v216, v12
	v_lshlrev_b32_e32 v13, 16, v13
	v_cvt_pk_bf16_f32 v93, v228, v228
	global_store_short v77, v93, s[18:19]
	v_fma_f32 v228, v228, v217, v13
	v_lshlrev_b32_e32 v14, 16, v14
	v_cvt_pk_bf16_f32 v94, v228, v228
	global_store_short v78, v94, s[18:19]
	v_fma_f32 v228, v228, v218, v14
	v_lshlrev_b32_e32 v15, 16, v15
	v_cvt_pk_bf16_f32 v95, v228, v228
	global_store_short v79, v95, s[18:19]
	v_fma_f32 v228, v228, v219, v15
	s_add_u32 s18, s18, 0x40000
	s_addc_u32 s19, s19, 0
	s_waitcnt vmcnt(32)
	v_lshlrev_b32_e32 v16, 16, v16
	v_cvt_pk_bf16_f32 v80, v228, v228
	global_store_short v64, v80, s[18:19]
	v_fma_f32 v228, v228, v220, v16
	v_lshlrev_b32_e32 v17, 16, v17
	v_cvt_pk_bf16_f32 v81, v228, v228
	global_store_short v65, v81, s[18:19]
	v_fma_f32 v228, v228, v221, v17
	v_lshlrev_b32_e32 v18, 16, v18
	v_cvt_pk_bf16_f32 v82, v228, v228
	global_store_short v66, v82, s[18:19]
	v_fma_f32 v228, v228, v222, v18
	v_lshlrev_b32_e32 v19, 16, v19
	v_cvt_pk_bf16_f32 v83, v228, v228
	global_store_short v67, v83, s[18:19]
	v_fma_f32 v228, v228, v223, v19
	v_lshlrev_b32_e32 v20, 16, v20
	v_cvt_pk_bf16_f32 v84, v228, v228
	global_store_short v68, v84, s[18:19]
	v_fma_f32 v228, v228, v224, v20
	v_lshlrev_b32_e32 v21, 16, v21
	v_cvt_pk_bf16_f32 v85, v228, v228
	global_store_short v69, v85, s[18:19]
	v_fma_f32 v228, v228, v225, v21
	v_lshlrev_b32_e32 v22, 16, v22
	v_cvt_pk_bf16_f32 v86, v228, v228
	global_store_short v70, v86, s[18:19]
	v_fma_f32 v228, v228, v226, v22
	v_lshlrev_b32_e32 v23, 16, v23
	v_cvt_pk_bf16_f32 v87, v228, v228
	global_store_short v71, v87, s[18:19]
	v_fma_f32 v228, v228, v227, v23
	v_lshlrev_b32_e32 v24, 16, v24
	v_cvt_pk_bf16_f32 v88, v228, v228
	global_store_short v72, v88, s[18:19]
	v_fma_f32 v228, v228, v238, v24
	v_lshlrev_b32_e32 v25, 16, v25
	v_cvt_pk_bf16_f32 v89, v228, v228
	global_store_short v73, v89, s[18:19]
	v_fma_f32 v228, v228, v239, v25
	v_lshlrev_b32_e32 v26, 16, v26
	v_cvt_pk_bf16_f32 v90, v228, v228
	global_store_short v74, v90, s[18:19]
	v_fma_f32 v228, v228, v240, v26
	v_lshlrev_b32_e32 v27, 16, v27
	v_cvt_pk_bf16_f32 v91, v228, v228
	global_store_short v75, v91, s[18:19]
	v_fma_f32 v228, v228, v241, v27
	v_lshlrev_b32_e32 v28, 16, v28
	v_cvt_pk_bf16_f32 v92, v228, v228
	global_store_short v76, v92, s[18:19]
	v_fma_f32 v228, v228, v242, v28
	v_lshlrev_b32_e32 v29, 16, v29
	v_cvt_pk_bf16_f32 v93, v228, v228
	global_store_short v77, v93, s[18:19]
	v_fma_f32 v228, v228, v243, v29
	v_lshlrev_b32_e32 v30, 16, v30
	v_cvt_pk_bf16_f32 v94, v228, v228
	global_store_short v78, v94, s[18:19]
	v_fma_f32 v228, v228, v244, v30
	v_lshlrev_b32_e32 v31, 16, v31
	v_cvt_pk_bf16_f32 v95, v228, v228
	global_store_short v79, v95, s[18:19]
	v_fma_f32 v228, v228, v245, v31
	s_add_u32 s18, s18, 0x40000
	s_addc_u32 s19, s19, 0
	s_lshl_b32 s11, s8, 15
	s_lshl_b32 s13, s9, 2
	s_add_i32 s11, s11, s13
	s_add_u32 s16, s4, 0x4600000
	s_addc_u32 s17, s5, 0
	s_add_u32 s16, s16, s11
	s_addc_u32 s17, s17, 0
	v_lshlrev_b32_e32 v229, 9, v236
	global_store_dword v229, v228, s[16:17]
	s_mov_b32 s8, s74
